# baseline (speedup 1.0000x reference)
; #define LAS __attribute__((address_space(3)))
; DI int my_tid() { int t = threadIdx.x; asm volatile("" : "+v"(t)); return t; }
; DI void phase_mixers(int l_, unsigned* ctr, LAS unsigned char* lds) {
;     ...
;   volatile LAS int* slot = (volatile LAS int*)(lds + LDS_BYTES - 16);
;   int nxt = 0;
;   if (my_tid() == 0) nxt = (int)__hip_atomic_fetch_add(ctr, 1u, __ATOMIC_RELAXED, __HIP_MEMORY_SCOPE_AGENT);
;   for (;;) {
;     __syncthreads();
;     if (my_tid() == 0) *slot = nxt;
;     __syncthreads();
;     const int it = __builtin_amdgcn_readfirstlane(*slot);
;     if (it >= NIT) break;
;     if (my_tid() == 0) nxt = (int)__hip_atomic_fetch_add(ctr, 1u, __ATOMIC_RELAXED, __HIP_MEMORY_SCOPE_AGENT);
;     int r = it; { int lv = l; asm volatile("" : "+v"(lv)); l = __builtin_amdgcn_readfirstlane(lv); }
;     const __attribute__((address_space(4))) void* kpi = (const __attribute__((address_space(4))) void*)__builtin_amdgcn_kernarg_segment_ptr();
;     asm volatile("" : "+s"(kpi));
;     CP& p = *(CP*)kpi;
;     if (r < N_MEM) { mix_mem(p, l, r, lds); continue; } r -= N_MEM;
;     if (r < N_SB) { mix_sb(p, l, r, lds); continue; } r -= N_SB;
;     if (r < N_G) { mix_gmlp(p, l, r, lds); continue; } r -= N_G;
;     if (r < N_C) { mix_conv(p, l, r, lds); continue; }
.LBB0_119:
	v_mov_b32_e32 v1, v144
	s_waitcnt vmcnt(0) lgkmcnt(0)
	s_barrier
	s_nop 0
	v_cmp_eq_u32_e32 vcc, 0, v1
	s_and_saveexec_b64 s[8:9], vcc
	v_mov_b32_e32 v1, s95
	ds_write_b32 v1, v134
	s_or_b64 exec, exec, s[8:9]
	v_mov_b32_e32 v1, s95
	s_waitcnt lgkmcnt(0)
	s_barrier
	ds_read_b32 v1, v1
	s_waitcnt lgkmcnt(0)
	v_readfirstlane_b32 s74, v1
	s_cmpk_gt_i32 s74, 0x4d0
	s_cbranch_scc1 .LBB0_134
	s_movk_i32 s0, 0xfc4f
	s_cmpk_lt_i32 s74, 0x3b1
	s_cselect_b32 s0, 0xffffff8f, s0
	s_cmpk_lt_i32 s74, 0x191
	s_cselect_b32 s0, 0x237, s0
	s_cmpk_lt_i32 s74, 0x109
	s_cselect_b32 s0, 0x3c7, s0
	s_cmpk_lt_i32 s74, 1
	s_cselect_b32 s0, 0x4d0, s0
	s_add_i32 s74, s74, s0
	v_mov_b32_e32 v1, v144
	s_nop 0
	v_cmp_eq_u32_e32 vcc, 0, v1
	s_and_saveexec_b64 s[8:9], vcc
	s_cbranch_execz .LBB0_126
	s_mov_b64 s[12:13], exec
	v_mbcnt_lo_u32_b32 v1, s12, 0
	v_mbcnt_hi_u32_b32 v1, s13, v1
	v_cmp_eq_u32_e32 vcc, 0, v1
	s_and_saveexec_b64 s[10:11], vcc
	s_cbranch_execz .LBB0_125
	s_bcnt1_i32_b64 s0, s[12:13]
	v_mov_b32_e32 v2, s0
	global_atomic_add v2, v147, v2, s[62:63] sc0
